# P5 U units: gate loads first, k rows and A-fragment rows issued ahead of the barrier, wave 0 waits only for its 4 gate loads
# speedup vs baseline: 1.0015x; 1.0015x over previous
; DI float bf2f(unsigned short h) { return __uint_as_float(((unsigned)h) << 16); }
; DI unsigned pk2(float lo, float hi) { f32x2_t v = {lo, hi}; bf16x2_t b = __builtin_convertvector(v, bf16x2_t); return __builtin_bit_cast(unsigned, b); }
; DI f32x4 mfma16(bf16x8 a, bf16x8 b, f32x4 c) { return __builtin_amdgcn_mfma_f32_16x16x32_bf16(a, b, c, 0, 0, 0); }
; DI void mlstm_u_unit(const Params& p, unsigned char* smem, const int tid, int u) {
;     ...
;     bf16x8 af[2][2];
; #pragma unroll
;     for (int mi = 0; mi < 2; ++mi)
; #pragma unroll
;         for (int ks = 0; ks < 2; ++ks) {
;             const int j0 = ks * 32 + (lane >> 4) * 8;
;             uint4 a = *(const uint4*)(kT + (((size_t)bh * 128 + c) * 128 + 32 * w + ((lane & 15) >> 2) * 8 + mi * 4 + (lane & 3)) * 64 + j0);
;             const unsigned* pa = (const unsigned*)&a;
;             uint4 o;
;             unsigned* po = (unsigned*)&o;
; #pragma unroll
;             for (int e = 0; e < 4; ++e) po[e] = pk2(bf2f(pa[e] & 0xffff) * wk[j0 + 2 * e], bf2f(pa[e] >> 16) * wk[j0 + 2 * e + 1]);
;             af[mi][ks] = __builtin_bit_cast(bf16x8, o);
;         }
; #pragma unroll
;     for (int nh = 0; nh < 2; ++nh) {
;         f32x4 acc[2][8];
; #pragma unroll
;         for (int mi = 0; mi < 2; ++mi)
; #pragma unroll
;             for (int ni = 0; ni < 8; ++ni) acc[mi][ni] = f32x4{0.f, 0.f, 0.f, 0.f};
; #pragma unroll
;         for (int ni = 0; ni < 8; ++ni)
; #pragma unroll
;             for (int ks = 0; ks < 2; ++ks)
; #pragma unroll
;                 for (int mi = 0; mi < 2; ++mi) acc[mi][ni] = mfma16(af[mi][ks], vfr[nh][ni][ks], acc[mi][ni]);
.LBB0_575:
	s_or_b64 exec, exec, s[16:17]
	s_waitcnt lgkmcnt(0)
	v_mov_b64_e32 v[130:131], v[222:223]
	v_mov_b64_e32 v[132:133], v[224:225]
	v_mov_b64_e32 v[164:165], v[226:227]
	v_mov_b64_e32 v[166:167], v[228:229]
	v_mov_b64_e32 v[168:169], v[230:231]
	v_mov_b64_e32 v[170:171], v[232:233]
	v_mov_b64_e32 v[172:173], v[234:235]
	v_mov_b64_e32 v[174:175], v[236:237]
	ds_read_b128 v[176:179], v149
	ds_read_b128 v[184:187], v149 offset:16
	ds_read_b128 v[188:191], v149 offset:128
	ds_read_b128 v[192:195], v149 offset:144
	v_add_u32_e32 v138, s90, v138
	v_mov_b32_e32 v161, v145
	v_lshl_add_u64 v[158:159], v[158:159], 0, s[6:7]
	v_lshlrev_b32_e32 v128, 16, v130
	v_and_b32_e32 v129, 0xffff0000, v130
	v_lshlrev_b32_e32 v130, 16, v131
	v_and_b32_e32 v131, 0xffff0000, v131
	v_lshlrev_b32_e32 v134, 16, v132
	v_and_b32_e32 v135, 0xffff0000, v132
	v_lshlrev_b32_e32 v132, 16, v133
	v_and_b32_e32 v133, 0xffff0000, v133
	v_lshlrev_b32_e32 v180, 16, v164
	v_and_b32_e32 v181, 0xffff0000, v164
	v_lshlrev_b32_e32 v182, 16, v165
	v_and_b32_e32 v183, 0xffff0000, v165
	v_lshlrev_b32_e32 v164, 16, v168
	v_and_b32_e32 v165, 0xffff0000, v168
	v_lshlrev_b32_e32 v168, 16, v169
	v_and_b32_e32 v169, 0xffff0000, v169
	v_lshlrev_b32_e32 v200, 16, v170
	v_and_b32_e32 v201, 0xffff0000, v170
	v_lshlrev_b32_e32 v170, 16, v171
	v_and_b32_e32 v171, 0xffff0000, v171
	s_waitcnt lgkmcnt(3)
	v_pk_mul_f32 v[128:129], v[176:177], v[128:129]
	v_pk_mul_f32 v[164:165], v[176:177], v[164:165]
	v_pk_mul_f32 v[130:131], v[178:179], v[130:131]
	v_pk_mul_f32 v[168:169], v[178:179], v[168:169]
	s_waitcnt lgkmcnt(2)
	v_pk_mul_f32 v[134:135], v[184:185], v[134:135]
	v_pk_mul_f32 v[176:177], v[184:185], v[200:201]
	v_pk_mul_f32 v[178:179], v[186:187], v[132:133]
	v_pk_mul_f32 v[170:171], v[186:187], v[170:171]
	v_cvt_pk_bf16_f32 v132, v128, v129
	v_cvt_pk_bf16_f32 v133, v130, v131
	v_cvt_pk_bf16_f32 v134, v134, v135
	v_cvt_pk_bf16_f32 v135, v178, v179
	v_cvt_pk_bf16_f32 v128, v164, v165
	v_cvt_pk_bf16_f32 v129, v168, v169
	v_cvt_pk_bf16_f32 v130, v176, v177
	v_cvt_pk_bf16_f32 v131, v170, v171
	v_lshlrev_b32_e32 v196, 16, v166
	v_and_b32_e32 v197, 0xffff0000, v166
	v_lshlrev_b32_e32 v198, 16, v167
	v_and_b32_e32 v199, 0xffff0000, v167
	v_lshlrev_b32_e32 v176, 16, v172
	v_and_b32_e32 v177, 0xffff0000, v172
	v_lshlrev_b32_e32 v184, 16, v173
	v_and_b32_e32 v185, 0xffff0000, v173
	v_lshlrev_b32_e32 v186, 16, v174
	v_and_b32_e32 v187, 0xffff0000, v174
	v_lshlrev_b32_e32 v200, 16, v175
	v_and_b32_e32 v201, 0xffff0000, v175
	v_mfma_f32_16x16x32_bf16 v[164:167], v[132:135], v[116:119], 0
	v_mfma_f32_16x16x32_bf16 v[172:175], v[128:131], v[116:119], 0
	s_waitcnt lgkmcnt(1)
	v_pk_mul_f32 v[116:117], v[188:189], v[180:181]
	v_pk_mul_f32 v[180:181], v[188:189], v[176:177]
	v_pk_mul_f32 v[118:119], v[190:191], v[182:183]
	v_pk_mul_f32 v[182:183], v[190:191], v[184:185]
	s_waitcnt lgkmcnt(0)
	v_pk_mul_f32 v[188:189], v[192:193], v[196:197]
	v_pk_mul_f32 v[192:193], v[192:193], v[186:187]
	v_pk_mul_f32 v[190:191], v[194:195], v[198:199]
	v_pk_mul_f32 v[194:195], v[194:195], v[200:201]
	v_cvt_pk_bf16_f32 v116, v116, v117
	v_mfma_f32_16x16x32_bf16 v[184:187], v[132:135], v[108:111], 0
	v_cvt_pk_bf16_f32 v117, v118, v119
	v_cvt_pk_bf16_f32 v118, v188, v189
	v_cvt_pk_bf16_f32 v119, v190, v191
	v_mfma_f32_16x16x32_bf16 v[188:191], v[128:131], v[108:111], 0
	v_cvt_pk_bf16_f32 v108, v180, v181
	v_cvt_pk_bf16_f32 v109, v182, v183
	v_cvt_pk_bf16_f32 v110, v192, v193
	v_cvt_pk_bf16_f32 v111, v194, v195
	v_mfma_f32_16x16x32_bf16 v[168:171], v[132:135], v[124:127], 0
	v_mfma_f32_16x16x32_bf16 v[124:127], v[128:131], v[124:127], 0
	v_mfma_f32_16x16x32_bf16 v[168:171], v[116:119], v[64:67], v[168:171]
	v_mfma_f32_16x16x32_bf16 v[64:67], v[108:111], v[64:67], v[124:127]
	v_mfma_f32_16x16x32_bf16 v[124:127], v[116:119], v[68:71], v[164:167]
	s_nop 5
	v_cvt_pk_bf16_f32 v168, v168, v169
	v_cvt_pk_bf16_f32 v169, v170, v171
	v_cvt_pk_bf16_f32 v170, v64, v65
	v_mfma_f32_16x16x32_bf16 v[68:71], v[108:111], v[68:71], v[172:175]
	v_lshlrev_b64 v[64:65], 16, v[162:163]
	v_cvt_pk_bf16_f32 v171, v66, v67
	v_lshl_add_u64 v[162:163], v[154:155], 0, v[64:65]
	v_mfma_f32_16x16x32_bf16 v[172:175], v[132:135], v[84:87], 0
	v_mfma_f32_16x16x32_bf16 v[84:87], v[128:131], v[84:87], 0
	v_mfma_f32_16x16x32_bf16 v[172:175], v[116:119], v[76:79], v[172:175]
	v_mfma_f32_16x16x32_bf16 v[76:79], v[108:111], v[76:79], v[84:87]
	v_mfma_f32_16x16x32_bf16 v[84:87], v[132:135], v[72:75], 0
	v_mfma_f32_16x16x32_bf16 v[72:75], v[128:131], v[72:75], 0
	v_mfma_f32_16x16x32_bf16 v[84:87], v[116:119], v[92:95], v[84:87]
	v_mfma_f32_16x16x32_bf16 v[72:75], v[108:111], v[92:95], v[72:75]
	v_mfma_f32_16x16x32_bf16 v[92:95], v[132:135], v[100:103], 0
	v_mfma_f32_16x16x32_bf16 v[100:103], v[128:131], v[100:103], 0
	v_mfma_f32_16x16x32_bf16 v[92:95], v[116:119], v[104:107], v[92:95]
	v_mfma_f32_16x16x32_bf16 v[100:103], v[108:111], v[104:107], v[100:103]
	v_mfma_f32_16x16x32_bf16 v[104:107], v[132:135], v[96:99], 0
	v_mfma_f32_16x16x32_bf16 v[96:99], v[128:131], v[96:99], 0
	v_mfma_f32_16x16x32_bf16 v[104:107], v[116:119], v[88:91], v[104:107]
	v_mfma_f32_16x16x32_bf16 v[88:91], v[108:111], v[88:91], v[96:99]
	v_mfma_f32_16x16x32_bf16 v[96:99], v[132:135], v[60:63], 0
	v_mfma_f32_16x16x32_bf16 v[60:63], v[128:131], v[60:63], 0
	v_mfma_f32_16x16x32_bf16 v[64:67], v[116:119], v[56:59], v[96:99]
	v_mfma_f32_16x16x32_bf16 v[56:59], v[108:111], v[56:59], v[60:63]
	s_nop 4
	v_cvt_pk_bf16_f32 v96, v124, v125
	v_cvt_pk_bf16_f32 v98, v68, v69
	v_cvt_pk_bf16_f32 v99, v70, v71
	v_mfma_f32_16x16x32_bf16 v[60:63], v[132:135], v[52:55], 0
	v_cvt_pk_bf16_f32 v64, v64, v65
; DI f32x4 mfma16(bf16x8 a, bf16x8 b, f32x4 c) { return __builtin_amdgcn_mfma_f32_16x16x32_bf16(a, b, c, 0, 0, 0); }
; DI uint4 pk8(f32x4 a, f32x4 b) { return make_uint4(pk2(a[0], a[1]), pk2(a[2], a[3]), pk2(b[0], b[1]), pk2(b[2], b[3])); }
; DI void mlstm_u_unit(const Params& p, unsigned char* smem, const int tid, int u) {
;     ...
; #pragma unroll
;     for (int nh = 0; nh < 2; ++nh) {
;         f32x4 acc[2][8];
; #pragma unroll
;         for (int mi = 0; mi < 2; ++mi)
; #pragma unroll
;             for (int ni = 0; ni < 8; ++ni) acc[mi][ni] = f32x4{0.f, 0.f, 0.f, 0.f};
; #pragma unroll
;         for (int ni = 0; ni < 8; ++ni)
; #pragma unroll
;             for (int ks = 0; ks < 2; ++ks)
; #pragma unroll
;                 for (int mi = 0; mi < 2; ++mi) acc[mi][ni] = mfma16(af[mi][ks], vfr[nh][ni][ks], acc[mi][ni]);
; #pragma unroll
;         for (int ni = 0; ni < 8; ++ni) {
;             const int dv = nh * 128 + ni * 16 + (lane & 15), d = 32 * w + (lane >> 4) * 8;
;             *(uint4*)(UT + (((size_t)bh * 128 + c) * 256 + dv) * 128 + d) = pk8(acc[0][ni], acc[1][ni]);
;         }
;     }
;     __syncthreads();
	v_cvt_pk_bf16_f32 v65, v66, v67
	v_cvt_pk_bf16_f32 v66, v56, v57
	v_mfma_f32_16x16x32_bf16 v[52:55], v[128:131], v[52:55], 0
	v_cvt_pk_bf16_f32 v67, v58, v59
	v_cvt_pk_bf16_f32 v97, v126, v127
	v_mfma_f32_16x16x32_bf16 v[60:63], v[116:119], v[48:51], v[60:63]
	v_mfma_f32_16x16x32_bf16 v[48:51], v[108:111], v[48:51], v[52:55]
	v_mfma_f32_16x16x32_bf16 v[52:55], v[132:135], v[44:47], 0
	s_nop 5
	v_cvt_pk_bf16_f32 v56, v60, v61
	v_cvt_pk_bf16_f32 v59, v50, v51
	v_cvt_pk_bf16_f32 v57, v62, v63
	v_mfma_f32_16x16x32_bf16 v[44:47], v[128:131], v[44:47], 0
	v_cvt_pk_bf16_f32 v58, v48, v49
	v_mfma_f32_16x16x32_bf16 v[52:55], v[116:119], v[40:43], v[52:55]
	v_mfma_f32_16x16x32_bf16 v[40:43], v[108:111], v[40:43], v[44:47]
	v_mfma_f32_16x16x32_bf16 v[44:47], v[132:135], v[36:39], 0
	s_nop 5
	v_cvt_pk_bf16_f32 v48, v52, v53
	v_cvt_pk_bf16_f32 v50, v40, v41
	v_cvt_pk_bf16_f32 v51, v42, v43
	v_mfma_f32_16x16x32_bf16 v[36:39], v[128:131], v[36:39], 0
	v_cvt_pk_bf16_f32 v49, v54, v55
	v_mfma_f32_16x16x32_bf16 v[176:179], v[132:135], v[120:123], 0
	v_mfma_f32_16x16x32_bf16 v[120:123], v[128:131], v[120:123], 0
	v_mfma_f32_16x16x32_bf16 v[44:47], v[116:119], v[32:35], v[44:47]
	v_mfma_f32_16x16x32_bf16 v[32:35], v[108:111], v[32:35], v[36:39]
	v_mfma_f32_16x16x32_bf16 v[36:39], v[132:135], v[28:31], 0
	s_nop 5
	v_cvt_pk_bf16_f32 v40, v44, v45
	v_cvt_pk_bf16_f32 v43, v34, v35
	v_cvt_pk_bf16_f32 v41, v46, v47
	v_mfma_f32_16x16x32_bf16 v[28:31], v[128:131], v[28:31], 0
	v_cvt_pk_bf16_f32 v42, v32, v33
	v_mfma_f32_16x16x32_bf16 v[164:167], v[116:119], v[80:83], v[176:179]
	v_mfma_f32_16x16x32_bf16 v[80:83], v[108:111], v[80:83], v[120:123]
	s_nop 1
	v_lshl_add_u64 v[176:177], v[162:163], 0, v[144:145]
	v_add_co_u32_e32 v124, vcc, s24, v176
	v_mfma_f32_16x16x32_bf16 v[120:123], v[116:119], v[112:115], v[184:187]
	s_nop 0
	v_addc_co_u32_e32 v125, vcc, 0, v177, vcc
	v_cvt_pk_bf16_f32 v68, v164, v165
	v_mfma_f32_16x16x32_bf16 v[112:115], v[108:111], v[112:115], v[188:191]
	v_cvt_pk_bf16_f32 v69, v166, v167
	v_cvt_pk_bf16_f32 v70, v80, v81
	v_cvt_pk_bf16_f32 v71, v82, v83
	v_mfma_f32_16x16x32_bf16 v[36:39], v[116:119], v[24:27], v[36:39]
	v_add_co_u32_e32 v80, vcc, s26, v176
	global_store_dwordx4 v[124:125], v[68:71], off
	v_mfma_f32_16x16x32_bf16 v[24:27], v[108:111], v[24:27], v[28:31]
	v_addc_co_u32_e32 v81, vcc, 0, v177, vcc
	v_cvt_pk_bf16_f32 v68, v120, v121
	v_mfma_f32_16x16x32_bf16 v[28:31], v[132:135], v[20:23], 0
	v_cvt_pk_bf16_f32 v69, v122, v123
	v_cvt_pk_bf16_f32 v70, v112, v113
	v_cvt_pk_bf16_f32 v71, v114, v115
	v_mfma_f32_16x16x32_bf16 v[20:23], v[128:131], v[20:23], 0
	global_store_dwordx4 v[80:81], v[68:71], off offset:-4096
	v_cvt_pk_bf16_f32 v35, v26, v27
	v_cvt_pk_bf16_f32 v34, v24, v25
	v_cvt_pk_bf16_f32 v68, v172, v173
	v_cvt_pk_bf16_f32 v69, v174, v175
	v_cvt_pk_bf16_f32 v70, v76, v77
	v_cvt_pk_bf16_f32 v71, v78, v79
	global_store_dwordx4 v[80:81], v[68:71], off
	v_mfma_f32_16x16x32_bf16 v[28:31], v[116:119], v[16:19], v[28:31]
	v_cvt_pk_bf16_f32 v32, v36, v37
	v_cvt_pk_bf16_f32 v70, v72, v73
	v_add_co_u32_e32 v72, vcc, s28, v176
	v_mfma_f32_16x16x32_bf16 v[16:19], v[108:111], v[16:19], v[20:23]
	v_cvt_pk_bf16_f32 v68, v84, v85
	v_cvt_pk_bf16_f32 v69, v86, v87
	v_cvt_pk_bf16_f32 v71, v74, v75
	v_mfma_f32_16x16x32_bf16 v[20:23], v[132:135], v[12:15], 0
	v_addc_co_u32_e32 v73, vcc, 0, v177, vcc
	global_store_dwordx4 v[72:73], v[68:71], off offset:-4096
	v_mfma_f32_16x16x32_bf16 v[12:15], v[128:131], v[12:15], 0
	s_nop 0
	v_cvt_pk_bf16_f32 v27, v18, v19
	v_cvt_pk_bf16_f32 v68, v92, v93
	v_cvt_pk_bf16_f32 v69, v94, v95
	v_cvt_pk_bf16_f32 v70, v100, v101
	v_cvt_pk_bf16_f32 v71, v102, v103
	global_store_dwordx4 v[72:73], v[68:71], off
	v_add_co_u32_e32 v72, vcc, s31, v176
	v_mfma_f32_16x16x32_bf16 v[20:23], v[116:119], v[8:11], v[20:23]
	s_nop 0
	v_addc_co_u32_e32 v73, vcc, 0, v177, vcc
	v_add_co_u32_e32 v60, vcc, s34, v176
	v_mfma_f32_16x16x32_bf16 v[8:11], v[108:111], v[8:11], v[12:15]
	s_nop 0
	v_addc_co_u32_e32 v61, vcc, 0, v177, vcc
	v_add_co_u32_e32 v44, vcc, s35, v176
	v_mfma_f32_16x16x32_bf16 v[12:15], v[132:135], v[4:7], 0
	s_nop 0
	v_addc_co_u32_e32 v45, vcc, 0, v177, vcc
	s_nop 1
	v_cvt_pk_bf16_f32 v18, v8, v9
	v_mfma_f32_16x16x32_bf16 v[4:7], v[128:131], v[4:7], 0
	v_cvt_pk_bf16_f32 v19, v10, v11
	v_cvt_pk_bf16_f32 v24, v28, v29
	v_add_co_u32_e32 v28, vcc, s36, v176
	v_mfma_f32_16x16x32_bf16 v[8:11], v[116:119], v[0:3], v[12:15]
	s_nop 0
	v_addc_co_u32_e32 v29, vcc, 0, v177, vcc
	v_cmp_lt_i32_e32 vcc, s37, v138
	v_mfma_f32_16x16x32_bf16 v[0:3], v[108:111], v[0:3], v[4:7]
	v_cvt_pk_bf16_f32 v68, v104, v105
	v_cvt_pk_bf16_f32 v69, v106, v107
	v_cvt_pk_bf16_f32 v70, v88, v89
	v_cvt_pk_bf16_f32 v71, v90, v91
	v_cvt_pk_bf16_f32 v33, v38, v39
	v_cvt_pk_bf16_f32 v25, v30, v31
	v_cvt_pk_bf16_f32 v26, v16, v17
	v_cvt_pk_bf16_f32 v16, v20, v21
	v_cvt_pk_bf16_f32 v17, v22, v23
	v_cvt_pk_bf16_f32 v8, v8, v9
	v_cvt_pk_bf16_f32 v9, v10, v11
	v_cvt_pk_bf16_f32 v10, v0, v1
	v_cvt_pk_bf16_f32 v11, v2, v3
	v_lshl_add_u64 v[0:1], v[162:163], 0, v[160:161]
	s_or_b64 s[14:15], vcc, s[14:15]
	global_store_dwordx4 v[176:177], v[168:171], off
	global_store_dwordx4 v[124:125], v[96:99], off offset:-4096
	global_store_dwordx4 v[72:73], v[68:71], off offset:-4096
	global_store_dwordx4 v[72:73], v[64:67], off
	global_store_dwordx4 v[60:61], v[56:59], off offset:-4096
	global_store_dwordx4 v[60:61], v[48:51], off
	global_store_dwordx4 v[44:45], v[40:43], off offset:-4096
	global_store_dwordx4 v[44:45], v[32:35], off
	global_store_dwordx4 v[28:29], v[24:27], off offset:-4096
	global_store_dwordx4 v[28:29], v[16:19], off
	global_store_dwordx4 v[0:1], v[8:11], off
	s_barrier
	s_andn2_b64 exec, exec, s[14:15]
	s_cbranch_execz .LBB0_580
; DI void mlstm_u_unit(const Params& p, unsigned char* smem, const int tid, int u) {
;     unsigned char* ws = p.ws;
;     const int lane = tid & 63, w = tid >> 6;
;     const int bh = u >> 7, c = u & 127, b = bh >> 2, h = bh & 3;
;     float* wk = (float*)smem;
;     const bf16_t* kT = (const bf16_t*)(ws + 7 * U_ + U_ / 2);
;     const bf16_t* vT = (const bf16_t*)(ws + 3 * U_);
;     bf16_t* UT = (bf16_t*)(ws + 1 * U_);
;     bf16x8 vfr[2][8][2];
; #pragma unroll
;     for (int nh = 0; nh < 2; ++nh)
; #pragma unroll
;         for (int ni = 0; ni < 8; ++ni) {
;             const bf16_t* vr = vT + (((size_t)bh * 128 + c) * 256 + nh * 128 + ni * 16 + (lane & 15)) * 64 + (lane >> 4) * 8;
;             vfr[nh][ni][0] = ld16(vr); vfr[nh][ni][1] = ld16(vr + 32);
;         }
;     if (tid < 64) {
;         const size_t o = (size_t)bh * 8192 + c * 64 + tid;
;         float bl = ((const float*)(ws + OFF_BLAST))[u];
;         float mn = ((const float*)(ws + OFF_MST))[bh * 132 + c + 1];
;         wk[tid] = __expf(bl - ((const float*)(ws + OFF_BCUM))[o] + ((const float*)(ws + OFF_IG))[o] - mn);
;     }
;     __syncthreads();
;     {
;         const int d = tid >> 1, hf = tid & 1;
;         const bf16_t* kr = kT + (((size_t)bh * 128 + c) * 128 + d) * 64 + hf * 32;
;         float s = 0.f;
; #pragma unroll
;         for (int i = 0; i < 4; ++i) {
;             uint4 a = *(const uint4*)(kr + i * 8);
.LBB0_576:
	v_ashrrev_i32_e32 v128, 7, v138
	v_ashrrev_i32_e32 v129, 31, v128
	v_and_b32_e32 v130, 0x7f, v138
	s_and_saveexec_b64 s[16:17], s[0:1]
	s_cbranch_execz .Lp5u_a
	v_lshlrev_b64 v[242:243], 13, v[128:129]
	v_lshl_or_b32 v221, v130, 6, v242
	v_or_b32_e32 v242, v221, v136
	global_load_dword v238, v[158:159], off
	v_lshlrev_b64 v[242:243], 2, v[242:243]
	v_lshl_add_u64 v[244:245], s[10:11], 0, v[242:243]
	v_lshl_add_u64 v[242:243], s[88:89], 0, v[242:243]
	v_mov_b32_e32 v247, 0
	v_mov_b32_e32 v246, v130
	s_nop 0
	v_mad_u64_u32 v[246:247], s[18:19], v128, s29, v[246:247]
	v_ashrrev_i32_e32 v247, 31, v246
	v_lshl_add_u64 v[246:247], v[246:247], 2, s[70:71]
	v_add_co_u32_e32 v246, vcc, s30, v246
	s_nop 1
	v_addc_co_u32_e32 v247, vcc, 0, v247, vcc
	global_load_dword v239, v[244:245], off
	global_load_dword v240, v[242:243], off
	global_load_dword v241, v[246:247], off offset:4
.Lp5u_a:
	s_or_b64 exec, exec, s[16:17]
	v_lshlrev_b64 v[0:1], 15, v[128:129]
	v_lshl_or_b32 v0, v130, 8, v0
	v_or_b32_e32 v0, v0, v142
	v_lshlrev_b64 v[0:1], 7, v[0:1]
	v_lshl_add_u64 v[0:1], v[150:151], 0, v[0:1]
	v_add_co_u32_e32 v2, vcc, s3, v0
	global_load_dwordx4 v[124:127], v[0:1], off
	global_load_dwordx4 v[64:67], v[0:1], off offset:64
	global_load_dwordx4 v[116:119], v[0:1], off offset:2048
	global_load_dwordx4 v[68:71], v[0:1], off offset:2112
	v_addc_co_u32_e32 v3, vcc, 0, v1, vcc
	v_add_co_u32_e32 v4, vcc, s24, v0
	s_nop 1
	v_addc_co_u32_e32 v5, vcc, 0, v1, vcc
	v_add_co_u32_e32 v6, vcc, s25, v0
	global_load_dwordx4 v[80:83], v[2:3], off offset:64
	global_load_dwordx4 v[108:111], v[2:3], off offset:2048
	global_load_dwordx4 v[120:123], v[4:5], off offset:-4096
	global_load_dwordx4 v[84:87], v[4:5], off
	global_load_dwordx4 v[76:79], v[4:5], off offset:64
	global_load_dwordx4 v[72:75], v[4:5], off offset:2048
	v_addc_co_u32_e32 v7, vcc, 0, v1, vcc
	v_add_co_u32_e32 v8, vcc, s26, v0
	s_nop 1
	v_addc_co_u32_e32 v9, vcc, 0, v1, vcc
	global_load_dwordx4 v[92:95], v[4:5], off offset:2112
	global_load_dwordx4 v[100:103], v[8:9], off offset:-4096
	global_load_dwordx4 v[112:115], v[2:3], off offset:2112
	global_load_dwordx4 v[104:107], v[6:7], off offset:64
	global_load_dwordx4 v[96:99], v[6:7], off offset:2048
	global_load_dwordx4 v[88:91], v[6:7], off offset:2112
	global_load_dwordx4 v[60:63], v[8:9], off
	global_load_dwordx4 v[56:59], v[8:9], off offset:64
	global_load_dwordx4 v[52:55], v[8:9], off offset:2048
	global_load_dwordx4 v[48:51], v[8:9], off offset:2112
	v_add_co_u32_e32 v2, vcc, s27, v0
	s_nop 1
	v_addc_co_u32_e32 v3, vcc, 0, v1, vcc
	global_load_dwordx4 v[44:47], v[2:3], off
	global_load_dwordx4 v[40:43], v[2:3], off offset:64
	global_load_dwordx4 v[36:39], v[2:3], off offset:2048
	global_load_dwordx4 v[32:35], v[2:3], off offset:2112
	v_add_co_u32_e32 v2, vcc, 0x6000, v0
	s_nop 1
	v_addc_co_u32_e32 v3, vcc, 0, v1, vcc
	v_add_co_u32_e32 v0, vcc, 0x7000, v0
	global_load_dwordx4 v[28:31], v[2:3], off
	global_load_dwordx4 v[24:27], v[2:3], off offset:64
	global_load_dwordx4 v[20:23], v[2:3], off offset:2048
	global_load_dwordx4 v[16:19], v[2:3], off offset:2112
	v_addc_co_u32_e32 v1, vcc, 0, v1, vcc
	global_load_dwordx4 v[12:15], v[0:1], off
	global_load_dwordx4 v[8:11], v[0:1], off offset:64
	global_load_dwordx4 v[4:7], v[0:1], off offset:2048
	s_nop 0
	global_load_dwordx4 v[0:3], v[0:1], off offset:2112
	v_lshlrev_b64 v[162:163], 7, v[128:129]
	v_or_b32_e32 v162, v162, v130
	v_lshlrev_b64 v[128:129], 7, v[162:163]
	v_or_b32_e32 v130, v128, v140
	v_mov_b32_e32 v131, v129
	v_lshlrev_b64 v[132:133], 7, v[130:131]
	v_lshl_add_u64 v[172:173], v[152:153], 0, v[132:133]
	v_or_b32_e32 v248, v128, v146
	v_mov_b32_e32 v249, v129
	global_load_dwordx4 v[132:135], v[172:173], off
	global_load_dwordx4 v[164:167], v[172:173], off offset:16
	global_load_dwordx4 v[168:171], v[172:173], off offset:32
	v_or_b32_e32 v252, v128, v148
	global_load_dwordx4 v[172:175], v[172:173], off offset:48
	v_mov_b32_e32 v253, v129
	v_lshlrev_b64 v[248:249], 7, v[248:249]
	v_lshlrev_b64 v[252:253], 7, v[252:253]
	v_lshl_add_u64 v[248:249], v[156:157], 0, v[248:249]
	v_lshl_add_u64 v[252:253], v[156:157], 0, v[252:253]
	global_load_dwordx4 v[222:225], v[248:249], off
	global_load_dwordx4 v[226:229], v[248:249], off offset:64
	global_load_dwordx4 v[230:233], v[252:253], off
	global_load_dwordx4 v[234:237], v[252:253], off offset:64
	s_and_saveexec_b64 s[16:17], s[0:1]
	s_cbranch_execz .LBB0_578
	s_waitcnt vmcnt(40)
	v_sub_f32_e32 v238, v238, v239
	v_add_f32_e32 v238, v238, v240
	v_sub_f32_e32 v238, v238, v241
	v_mul_f32_e32 v238, 0x3fb8aa3b, v238
	v_exp_f32_e32 v238, v238
	s_nop 0
	ds_write_b32 v141, v238
; DI float bf2f(unsigned short h) { return __uint_as_float(((unsigned)h) << 16); }
; DI void mlstm_u_unit(const Params& p, unsigned char* smem, const int tid, int u) {
;     ...
;     __syncthreads();
;     {
;         const int d = tid >> 1, hf = tid & 1;
;         const bf16_t* kr = kT + (((size_t)bh * 128 + c) * 128 + d) * 64 + hf * 32;
;         float s = 0.f;
; #pragma unroll
;         for (int i = 0; i < 4; ++i) {
;             uint4 a = *(const uint4*)(kr + i * 8);
;             const unsigned* pa = (const unsigned*)&a;
; #pragma unroll
;             for (int e = 0; e < 4; ++e) { s += bf2f(pa[e] & 0xffff) * wk[hf * 32 + i * 8 + 2 * e] + bf2f(pa[e] >> 16) * wk[hf * 32 + i * 8 + 2 * e + 1]; }
;         }
;         s += __shfl_xor(s, 1, 64);
;         if (hf == 0) ((float*)(ws + OFF_NU))[((size_t)bh * 128 + c) * 128 + d] = s;
.LBB0_578:
	s_or_b64 exec, exec, s[16:17]
	s_waitcnt lgkmcnt(0)
	s_barrier
	ds_read_b128 v[176:179], v143
	ds_read_b128 v[184:187], v143 offset:16
	ds_read_b128 v[188:191], v143 offset:32
	ds_read_b128 v[192:195], v143 offset:48
	ds_read_b128 v[196:199], v143 offset:64
	ds_read_b128 v[200:203], v143 offset:80
	ds_read_b128 v[204:207], v143 offset:96
	ds_read_b128 v[208:211], v143 offset:112
	s_waitcnt vmcnt(7)
	v_lshlrev_b32_e32 v137, 16, v132
	v_and_b32_e32 v132, 0xffff0000, v132
	v_lshlrev_b32_e32 v139, 16, v133
	v_and_b32_e32 v133, 0xffff0000, v133
	s_waitcnt lgkmcnt(7)
	v_mul_f32_e32 v132, v177, v132
	v_lshlrev_b32_e32 v161, 16, v134
	v_and_b32_e32 v134, 0xffff0000, v134
	v_mul_f32_e32 v133, v179, v133
	v_fmac_f32_e32 v132, v176, v137
	v_lshlrev_b32_e32 v180, 16, v135
	v_and_b32_e32 v135, 0xffff0000, v135
	s_waitcnt lgkmcnt(6)
	v_mul_f32_e32 v134, v185, v134
	v_fmac_f32_e32 v133, v178, v139
	v_add_f32_e32 v132, 0, v132
	s_waitcnt vmcnt(6)
	v_lshlrev_b32_e32 v181, 16, v164
	v_and_b32_e32 v164, 0xffff0000, v164
	v_mul_f32_e32 v135, v187, v135
	v_fmac_f32_e32 v134, v184, v161
	v_add_f32_e32 v132, v132, v133
	v_lshlrev_b32_e32 v182, 16, v165
	v_and_b32_e32 v165, 0xffff0000, v165
	s_waitcnt lgkmcnt(5)
	v_mul_f32_e32 v164, v189, v164
	v_fmac_f32_e32 v135, v186, v180
	v_add_f32_e32 v132, v132, v134
	v_lshlrev_b32_e32 v183, 16, v166
	v_and_b32_e32 v166, 0xffff0000, v166
	v_mul_f32_e32 v165, v191, v165
	v_fmac_f32_e32 v164, v188, v181
	v_add_f32_e32 v132, v132, v135
	v_lshlrev_b32_e32 v212, 16, v167
	v_and_b32_e32 v167, 0xffff0000, v167
	s_waitcnt lgkmcnt(4)
	v_mul_f32_e32 v166, v193, v166
	v_fmac_f32_e32 v165, v190, v182
	v_add_f32_e32 v132, v132, v164
	s_waitcnt vmcnt(5)
	v_lshlrev_b32_e32 v213, 16, v168
	v_and_b32_e32 v168, 0xffff0000, v168
	v_mul_f32_e32 v167, v195, v167
	v_fmac_f32_e32 v166, v192, v183
	v_add_f32_e32 v132, v132, v165
	v_lshlrev_b32_e32 v214, 16, v169
	v_and_b32_e32 v169, 0xffff0000, v169
	s_waitcnt lgkmcnt(3)
	v_mul_f32_e32 v168, v197, v168
	v_fmac_f32_e32 v167, v194, v212
	v_add_f32_e32 v132, v132, v166
	v_lshlrev_b32_e32 v215, 16, v170
	v_and_b32_e32 v170, 0xffff0000, v170
	v_mul_f32_e32 v169, v199, v169
	v_fmac_f32_e32 v168, v196, v213
	v_add_f32_e32 v132, v132, v167
	v_lshlrev_b32_e32 v216, 16, v171
	v_and_b32_e32 v171, 0xffff0000, v171
	s_waitcnt lgkmcnt(2)
	v_mul_f32_e32 v170, v201, v170
	v_fmac_f32_e32 v169, v198, v214
	v_add_f32_e32 v132, v132, v168
	s_waitcnt vmcnt(0)
	v_lshlrev_b32_e32 v217, 16, v172
	v_and_b32_e32 v172, 0xffff0000, v172
	v_mul_f32_e32 v171, v203, v171
	v_fmac_f32_e32 v170, v200, v215
	v_add_f32_e32 v132, v132, v169
	v_lshlrev_b32_e32 v218, 16, v173
	v_and_b32_e32 v173, 0xffff0000, v173
	s_waitcnt lgkmcnt(1)
	v_mul_f32_e32 v172, v205, v172
	v_fmac_f32_e32 v171, v202, v216
	v_add_f32_e32 v132, v132, v170
	v_lshlrev_b32_e32 v219, 16, v174
	v_and_b32_e32 v174, 0xffff0000, v174
	v_mul_f32_e32 v173, v207, v173
	v_fmac_f32_e32 v172, v204, v217
	v_add_f32_e32 v132, v132, v171
	v_lshlrev_b32_e32 v220, 16, v175
	v_and_b32_e32 v175, 0xffff0000, v175
	s_waitcnt lgkmcnt(0)
	v_mul_f32_e32 v174, v209, v174
	v_fmac_f32_e32 v173, v206, v218
	v_add_f32_e32 v132, v132, v172
	v_mul_f32_e32 v175, v211, v175
	v_fmac_f32_e32 v174, v208, v219
	v_add_f32_e32 v132, v132, v173
	v_add_f32_e32 v132, v132, v174
	v_fmac_f32_e32 v175, v210, v220
	v_add_f32_e32 v132, v132, v175
	ds_bpermute_b32 v133, v147, v132
	s_and_saveexec_b64 s[16:17], s[4:5]
	s_cbranch_execz .LBB0_575
	v_lshl_add_u64 v[130:131], v[130:131], 2, s[12:13]
	s_waitcnt lgkmcnt(0)
	v_add_f32_e32 v132, v132, v133
	global_store_dword v[130:131], v132, off
	s_branch .LBB0_575
